# layer-0 pre-MLP RMSNorm fused: producer GEMM epilogue writes bf16(h) + row sumsq partials, gain folded into W1 conversion, MLP-up epilogue scales by rsqrt; norm phase bypassed
# baseline (speedup 1.0000x reference)
.LBB0_166:
	s_add_u32 s0, s38, 0xa000000
	s_addc_u32 s1, s39, 0
	v_writelane_b32 v254, s0, 10
	s_nop 1
	v_writelane_b32 v254, s1, 11
	s_add_u32 s0, s38, 0xa800000
	s_addc_u32 s1, s39, 0
	s_waitcnt lgkmcnt(0)
	s_cmpk_eq_i32 s26, 0x100
	s_cselect_b64 s[56:57], -1, 0
	s_cmpk_lg_i32 s26, 0x100
	s_cselect_b64 s[62:63], -1, 0
	v_writelane_b32 v254, s0, 12
	s_and_b64 vcc, exec, s[62:63]
	s_nop 0
	v_writelane_b32 v254, s1, 13
	s_cbranch_vccnz .LBB0_206
	s_cmp_lt_i32 s27, 64
	s_cbranch_scc1 .LBB0_206
	v_mov_b32_e32 v2, v160
	s_nop 0
	v_readfirstlane_b32 s0, v2
	s_ashr_i32 s1, s0, 6
	s_add_i32 s0, s91, 0xfffffe00
	s_add_i32 s1, s0, s1
	s_cmpk_gt_i32 s1, 0x7ff
	s_cbranch_scc1 .LBB0_187
	s_load_dwordx2 s[4:5], s[92:93], 0x40
	s_load_dwordx2 s[100:101], s[92:93], 0x38
	v_and_b32_e32 v3, 7, v2
	v_readlane_b32 s2, v254, 10
	v_lshlrev_b32_e32 v40, 2, v3
	v_bfe_u32 v41, v2, 3, 3
	v_lshlrev_b32_e32 v2, 4, v3
	v_mul_u32_u24_e32 v5, 0x420, v3
	v_mov_b32_e32 v3, 0
	v_readlane_b32 s3, v254, 11
	v_add_u32_e32 v4, s41, v2
	s_nop 0
	v_lshl_add_u64 v[34:35], s[2:3], 0, v[2:3]
	v_lshlrev_b32_e32 v2, 2, v41
	v_add3_u32 v42, s41, v5, v2
	v_mul_u32_u24_e32 v2, 0x84, v41
	s_lshl_b32 s2, s1, 5
	s_movk_i32 s3, 0x1000
	v_add_u32_e32 v43, v4, v2
	s_branch .LBB0_171
.LBB0_170:
	s_or_b64 exec, exec, s[8:9]
	v_lshlrev_b32_e32 v54, 2, v38
	global_load_dword v44, v54, s[100:101]
	global_load_dword v46, v54, s[100:101] offset:32
	global_load_dword v48, v54, s[100:101] offset:64
	global_load_dword v49, v54, s[100:101] offset:96
	global_load_dword v50, v54, s[100:101] offset:128
	global_load_dword v51, v54, s[100:101] offset:160
	global_load_dword v52, v54, s[100:101] offset:192
	global_load_dword v53, v54, s[100:101] offset:224
	s_waitcnt vmcnt(0)
	v_mul_f32_e32 v2, v2, v44
	v_mul_f32_e32 v3, v3, v44
	v_mul_f32_e32 v4, v4, v44
	v_mul_f32_e32 v5, v5, v44
	v_mul_f32_e32 v10, v10, v46
	v_mul_f32_e32 v11, v11, v46
	v_mul_f32_e32 v12, v12, v46
	v_mul_f32_e32 v13, v13, v46
	v_mul_f32_e32 v6, v6, v48
	v_mul_f32_e32 v7, v7, v48
	v_mul_f32_e32 v8, v8, v48
	v_mul_f32_e32 v9, v9, v48
	v_mul_f32_e32 v18, v18, v49
	v_mul_f32_e32 v19, v19, v49
	v_mul_f32_e32 v20, v20, v49
	v_mul_f32_e32 v21, v21, v49
	v_mul_f32_e32 v14, v14, v50
	v_mul_f32_e32 v15, v15, v50
	v_mul_f32_e32 v16, v16, v50
	v_mul_f32_e32 v17, v17, v50
	v_mul_f32_e32 v26, v26, v51
	v_mul_f32_e32 v27, v27, v51
	v_mul_f32_e32 v28, v28, v51
	v_mul_f32_e32 v29, v29, v51
	v_mul_f32_e32 v22, v22, v52
	v_mul_f32_e32 v23, v23, v52
	v_mul_f32_e32 v24, v24, v52
	v_mul_f32_e32 v25, v25, v52
	v_mul_f32_e32 v30, v30, v53
	v_mul_f32_e32 v31, v31, v53
	v_mul_f32_e32 v32, v32, v53
	v_mul_f32_e32 v33, v33, v53
	ds_write2_b32 v43, v2, v3 offset1:1
	ds_write2_b32 v43, v4, v5 offset0:2 offset1:3
	v_add_u32_e32 v2, 0x420, v43
	ds_write2_b32 v2, v10, v11 offset1:1
	v_add_u32_e32 v2, 0x428, v43
	ds_write2_b32 v2, v12, v13 offset1:1
	v_add_u32_e32 v2, 0x840, v43
	ds_write2_b32 v2, v6, v7 offset1:1
	v_add_u32_e32 v2, 0x848, v43
	ds_write2_b32 v2, v8, v9 offset1:1
	v_add_u32_e32 v2, 0xc60, v43
	ds_write2_b32 v2, v18, v19 offset1:1
	v_add_u32_e32 v2, 0xc68, v43
	ds_write2_b32 v2, v20, v21 offset1:1
	v_add_u32_e32 v2, 0x1080, v43
	ds_write2_b32 v2, v14, v15 offset1:1
	v_add_u32_e32 v2, 0x1088, v43
	ds_write2_b32 v2, v16, v17 offset1:1
	v_add_u32_e32 v2, 0x14a0, v43
	ds_write2_b32 v2, v26, v27 offset1:1
	v_add_u32_e32 v2, 0x14a8, v43
	ds_write2_b32 v2, v28, v29 offset1:1
	v_add_u32_e32 v2, 0x18c0, v43
	ds_write2_b32 v2, v22, v23 offset1:1
	v_add_u32_e32 v2, 0x18c8, v43
	ds_write2_b32 v2, v24, v25 offset1:1
	v_add_u32_e32 v2, 0x1ce0, v43
	ds_write2_b32 v2, v30, v31 offset1:1
	v_add_u32_e32 v2, 0x1ce8, v43
	ds_write2_b32 v2, v32, v33 offset1:1
	s_waitcnt lgkmcnt(0)
	s_sub_i32 s8, 0, s7
	ds_read2_b32 v[6:7], v42 offset0:33 offset1:41
	ds_read2_b32 v[8:9], v42 offset1:8
	ds_read2_b32 v[10:11], v42 offset0:66 offset1:74
	ds_read2_b32 v[12:13], v42 offset0:99 offset1:107
	ds_read2_b32 v[14:15], v42 offset0:132 offset1:140
	ds_read2_b32 v[16:17], v42 offset0:165 offset1:173
	ds_read2_b32 v[18:19], v42 offset0:198 offset1:206
	ds_read2_b32 v[20:21], v42 offset0:231 offset1:239
	s_add_i32 s8, s8, s2
	v_add_u32_e32 v24, s8, v41
	s_ashr_i32 s7, s6, 31
	v_ashrrev_i32_e32 v25, 31, v24
	v_lshl_add_u64 v[22:23], s[6:7], 1, v[34:35]
	v_lshlrev_b64 v[26:27], 11, v[24:25]
	s_waitcnt lgkmcnt(6)
	v_cvt_pk_bf16_f32 v2, v8, v6
	s_waitcnt lgkmcnt(4)
	v_cvt_pk_bf16_f32 v3, v10, v12
	s_waitcnt lgkmcnt(2)
	v_cvt_pk_bf16_f32 v4, v14, v16
	s_waitcnt lgkmcnt(0)
	v_cvt_pk_bf16_f32 v5, v18, v20
	v_lshl_add_u64 v[26:27], v[22:23], 0, v[26:27]
	v_add_u32_e32 v6, 8, v24
	global_store_dwordx4 v[26:27], v[2:5], off sc1
	s_add_i32 s6, s1, 0x600
	s_add_i32 s2, s2, 0xc000
	v_cvt_pk_bf16_f32 v2, v9, v7
	v_ashrrev_i32_e32 v7, 31, v6
	v_cvt_pk_bf16_f32 v3, v11, v13
	v_cvt_pk_bf16_f32 v4, v15, v17
	v_cvt_pk_bf16_f32 v5, v19, v21
	v_lshlrev_b64 v[6:7], 11, v[6:7]
	ds_read2_b32 v[8:9], v42 offset0:49 offset1:57
	ds_read2_b32 v[10:11], v42 offset0:16 offset1:24
	ds_read2_b32 v[12:13], v42 offset0:82 offset1:90
	ds_read2_b32 v[14:15], v42 offset0:115 offset1:123
	ds_read2_b32 v[16:17], v42 offset0:148 offset1:156
	ds_read2_b32 v[18:19], v42 offset0:181 offset1:189
	ds_read2_b32 v[20:21], v42 offset0:214 offset1:222
	ds_read2_b32 v[26:27], v42 offset0:247 offset1:255
	v_lshl_add_u64 v[6:7], v[22:23], 0, v[6:7]
	global_store_dwordx4 v[6:7], v[2:5], off sc1
	v_add_u32_e32 v6, 16, v24
	v_ashrrev_i32_e32 v7, 31, v6
	v_lshlrev_b64 v[6:7], 11, v[6:7]
	s_waitcnt lgkmcnt(6)
	v_cvt_pk_bf16_f32 v2, v10, v8
	s_waitcnt lgkmcnt(4)
	v_cvt_pk_bf16_f32 v3, v12, v14
	s_waitcnt lgkmcnt(2)
	v_cvt_pk_bf16_f32 v4, v16, v18
	s_waitcnt lgkmcnt(0)
	v_cvt_pk_bf16_f32 v5, v20, v26
	v_lshl_add_u64 v[6:7], v[22:23], 0, v[6:7]
	global_store_dwordx4 v[6:7], v[2:5], off sc1
	v_add_u32_e32 v6, 24, v24
	v_ashrrev_i32_e32 v7, 31, v6
	v_lshlrev_b64 v[6:7], 11, v[6:7]
	v_cvt_pk_bf16_f32 v2, v11, v9
	v_cvt_pk_bf16_f32 v3, v13, v15
	v_cvt_pk_bf16_f32 v4, v17, v19
	v_cvt_pk_bf16_f32 v5, v21, v27
	v_lshl_add_u64 v[6:7], v[22:23], 0, v[6:7]
	global_store_dwordx4 v[6:7], v[2:5], off sc1
	s_waitcnt lgkmcnt(0)
	s_cmpk_lt_i32 s1, 0x200
	s_mov_b32 s1, s6
	s_cbranch_scc0 .LBB0_187

.LBB0_425:
	v_lshl_or_b32 v140, s47, 8, v147
	v_lshl_add_u32 v144, s22, 8, v146
	v_ashrrev_i32_e32 v141, 31, v140
	v_or_b32_e32 v174, 16, v144
	v_or_b32_e32 v190, 32, v144
	v_or_b32_e32 v206, 48, v144
	v_lshlrev_b64 v[140:141], 2, v[140:141]
	v_ashrrev_i32_e32 v145, 31, v144
	v_ashrrev_i32_e32 v175, 31, v174
	v_ashrrev_i32_e32 v191, 31, v190
	v_ashrrev_i32_e32 v207, 31, v206
	v_lshl_add_u64 v[142:143], s[66:67], 0, v[140:141]
	v_lshlrev_b64 v[158:159], 12, v[144:145]
	v_lshlrev_b64 v[226:227], 12, v[174:175]
	v_lshlrev_b64 v[228:229], 12, v[190:191]
	v_lshlrev_b64 v[230:231], 12, v[206:207]
	v_lshl_add_u64 v[170:171], v[142:143], 0, v[158:159]
	v_lshl_add_u64 v[186:187], v[142:143], 0, v[226:227]
	v_lshl_add_u64 v[202:203], v[142:143], 0, v[228:229]
	v_lshl_add_u64 v[222:223], v[142:143], 0, v[230:231]
	global_load_dwordx4 v[154:157], v[170:171], off
	global_load_dwordx4 v[162:165], v[170:171], off offset:64
	global_load_dwordx4 v[166:169], v[170:171], off offset:512
	s_nop 0
	global_load_dwordx4 v[170:173], v[170:171], off offset:576
	s_nop 0
	global_load_dwordx4 v[174:177], v[186:187], off
	global_load_dwordx4 v[178:181], v[186:187], off offset:64
	global_load_dwordx4 v[182:185], v[186:187], off offset:512
	s_nop 0
	global_load_dwordx4 v[186:189], v[186:187], off offset:576
	s_nop 0
	global_load_dwordx4 v[190:193], v[202:203], off
	global_load_dwordx4 v[194:197], v[202:203], off offset:64
	global_load_dwordx4 v[198:201], v[202:203], off offset:512
	s_nop 0
	global_load_dwordx4 v[202:205], v[202:203], off offset:576
	s_nop 0
	global_load_dwordx4 v[206:209], v[222:223], off
	global_load_dwordx4 v[214:217], v[222:223], off offset:64
	global_load_dwordx4 v[218:221], v[222:223], off offset:512
	s_nop 0
	global_load_dwordx4 v[222:225], v[222:223], off offset:576
	v_lshl_add_u64 v[158:159], s[36:37], 0, v[158:159]
	v_lshl_add_u64 v[230:231], s[36:37], 0, v[230:231]
	v_lshl_add_u64 v[158:159], v[158:159], 0, v[140:141]
	v_lshl_add_u64 v[226:227], s[36:37], 0, v[226:227]
	v_lshl_add_u64 v[228:229], s[36:37], 0, v[228:229]
	v_lshl_add_u64 v[230:231], v[230:231], 0, v[140:141]
	v_lshl_add_u64 v[226:227], v[226:227], 0, v[140:141]
	v_lshl_add_u64 v[228:229], v[228:229], 0, v[140:141]
	s_andn2_b64 vcc, exec, s[4:5]
	s_mov_b64 s[4:5], -1
	s_waitcnt vmcnt(0)
	v_pk_add_f32 v[126:127], v[126:127], v[156:157]
	v_pk_add_f32 v[124:125], v[124:125], v[154:155]
	v_pk_add_f32 v[122:123], v[122:123], v[164:165]
	v_pk_add_f32 v[96:97], v[96:97], v[170:171]
	v_pk_add_f32 v[80:81], v[80:81], v[214:215]
	v_pk_add_f32 v[120:121], v[120:121], v[162:163]
	v_pk_add_f32 v[66:67], v[66:67], v[224:225]
	v_pk_add_f32 v[64:65], v[64:65], v[222:223]
	v_pk_add_f32 v[106:107], v[106:107], v[168:169]
	v_pk_add_f32 v[104:105], v[104:105], v[166:167]
	v_pk_add_f32 v[98:99], v[98:99], v[172:173]
	v_pk_add_f32 v[118:119], v[118:119], v[176:177]
	v_pk_add_f32 v[116:117], v[116:117], v[174:175]
	v_pk_add_f32 v[114:115], v[114:115], v[180:181]
	v_pk_add_f32 v[112:113], v[112:113], v[178:179]
	v_pk_add_f32 v[90:91], v[90:91], v[184:185]
	v_pk_add_f32 v[88:89], v[88:89], v[182:183]
	v_pk_add_f32 v[86:87], v[86:87], v[188:189]
	v_pk_add_f32 v[84:85], v[84:85], v[186:187]
	v_pk_add_f32 v[110:111], v[110:111], v[192:193]
	v_pk_add_f32 v[108:109], v[108:109], v[190:191]
	v_pk_add_f32 v[102:103], v[102:103], v[196:197]
	v_pk_add_f32 v[100:101], v[100:101], v[194:195]
	v_pk_add_f32 v[78:79], v[78:79], v[200:201]
	v_pk_add_f32 v[76:77], v[76:77], v[198:199]
	v_pk_add_f32 v[74:75], v[74:75], v[204:205]
	v_pk_add_f32 v[72:73], v[72:73], v[202:203]
	v_pk_add_f32 v[94:95], v[94:95], v[208:209]
	v_pk_add_f32 v[92:93], v[92:93], v[206:207]
	v_pk_add_f32 v[82:83], v[82:83], v[216:217]
	v_lshl_add_u32 v164, s22, 8, v146
	v_lshlrev_b32_e32 v165, 6, v164
	v_lshlrev_b32_e32 v164, 11, v164
	v_lshl_or_b32 v153, s47, 8, v147
	v_lshl_add_u32 v164, v153, 1, v164
	v_add_u32_e32 v164, 0x8000000, v164
	v_lshrrev_b32_e32 v153, 5, v153
	v_and_b32_e32 v162, 3, v153
	v_lshrrev_b32_e32 v153, 3, v153
	v_lshl_add_u32 v153, v153, 2, v162
	v_lshl_add_u32 v165, v153, 2, v165
	v_add_u32_e32 v165, 0xc200000, v165
	global_store_dwordx4 v[158:159], v[124:127], off sc1
	v_mul_f32_e32 v169, v124, v124
	v_fmac_f32_e32 v169, v125, v125
	v_fmac_f32_e32 v169, v126, v126
	v_fmac_f32_e32 v169, v127, v127
	v_cvt_pk_bf16_f32 v162, v124, v125
	v_cvt_pk_bf16_f32 v163, v126, v127
	global_store_dwordx2 v164, v[162:163], s[38:39]
	global_store_dwordx4 v[158:159], v[120:123], off offset:64 sc1
	v_fmac_f32_e32 v169, v120, v120
	v_fmac_f32_e32 v169, v121, v121
	v_fmac_f32_e32 v169, v122, v122
	v_fmac_f32_e32 v169, v123, v123
	v_cvt_pk_bf16_f32 v162, v120, v121
	v_cvt_pk_bf16_f32 v163, v122, v123
	global_store_dwordx2 v164, v[162:163], s[38:39] offset:32
	global_store_dwordx4 v[158:159], v[104:107], off offset:512 sc1
	v_fmac_f32_e32 v169, v104, v104
	v_fmac_f32_e32 v169, v105, v105
	v_fmac_f32_e32 v169, v106, v106
	v_fmac_f32_e32 v169, v107, v107
	v_cvt_pk_bf16_f32 v162, v104, v105
	v_cvt_pk_bf16_f32 v163, v106, v107
	global_store_dwordx2 v164, v[162:163], s[38:39] offset:256
	global_store_dwordx4 v[158:159], v[96:99], off offset:576 sc1
	v_fmac_f32_e32 v169, v96, v96
	v_fmac_f32_e32 v169, v97, v97
	v_fmac_f32_e32 v169, v98, v98
	v_fmac_f32_e32 v169, v99, v99
	v_cvt_pk_bf16_f32 v162, v96, v97
	v_cvt_pk_bf16_f32 v163, v98, v99
	global_store_dwordx2 v164, v[162:163], s[38:39] offset:288
	v_mov_b32_e32 v168, v169
	s_nop 1
	v_permlane16_swap_b32_e32 v168, v169
	v_add_f32_e32 v169, v168, v169
	v_mov_b32_e32 v168, v169
	s_nop 1
	v_permlane32_swap_b32_e32 v168, v169
	v_add_f32_e32 v169, v168, v169
	global_store_dword v165, v169, s[38:39]
	global_store_dwordx4 v[226:227], v[116:119], off sc1
	v_mul_f32_e32 v170, v116, v116
	v_fmac_f32_e32 v170, v117, v117
	v_fmac_f32_e32 v170, v118, v118
	v_fmac_f32_e32 v170, v119, v119
	v_cvt_pk_bf16_f32 v162, v116, v117
	v_cvt_pk_bf16_f32 v163, v118, v119
	v_add_u32_e32 v153, 0x8000, v164
	global_store_dwordx2 v153, v[162:163], s[38:39]
	global_store_dwordx4 v[226:227], v[112:115], off offset:64 sc1
	v_fmac_f32_e32 v170, v112, v112
	v_fmac_f32_e32 v170, v113, v113
	v_fmac_f32_e32 v170, v114, v114
	v_fmac_f32_e32 v170, v115, v115
	v_cvt_pk_bf16_f32 v162, v112, v113
	v_cvt_pk_bf16_f32 v163, v114, v115
	v_add_u32_e32 v153, 0x8000, v164
	global_store_dwordx2 v153, v[162:163], s[38:39] offset:32
	global_store_dwordx4 v[226:227], v[88:91], off offset:512 sc1
	v_fmac_f32_e32 v170, v88, v88
	v_fmac_f32_e32 v170, v89, v89
	v_fmac_f32_e32 v170, v90, v90
	v_fmac_f32_e32 v170, v91, v91
	v_cvt_pk_bf16_f32 v162, v88, v89
	v_cvt_pk_bf16_f32 v163, v90, v91
	v_add_u32_e32 v153, 0x8000, v164
	global_store_dwordx2 v153, v[162:163], s[38:39] offset:256
	global_store_dwordx4 v[226:227], v[84:87], off offset:576 sc1
	v_fmac_f32_e32 v170, v84, v84
	v_fmac_f32_e32 v170, v85, v85
	v_fmac_f32_e32 v170, v86, v86
	v_fmac_f32_e32 v170, v87, v87
	v_cvt_pk_bf16_f32 v162, v84, v85
	v_cvt_pk_bf16_f32 v163, v86, v87
	v_add_u32_e32 v153, 0x8000, v164
	global_store_dwordx2 v153, v[162:163], s[38:39] offset:288
	v_mov_b32_e32 v168, v170
	s_nop 1
	v_permlane16_swap_b32_e32 v168, v170
	v_add_f32_e32 v170, v168, v170
	v_mov_b32_e32 v168, v170
	s_nop 1
	v_permlane32_swap_b32_e32 v168, v170
	v_add_f32_e32 v170, v168, v170
	v_add_u32_e32 v153, 0x400, v165
	global_store_dword v153, v170, s[38:39]
	global_store_dwordx4 v[228:229], v[108:111], off sc1
	v_mul_f32_e32 v171, v108, v108
	v_fmac_f32_e32 v171, v109, v109
	v_fmac_f32_e32 v171, v110, v110
	v_fmac_f32_e32 v171, v111, v111
	v_cvt_pk_bf16_f32 v162, v108, v109
	v_cvt_pk_bf16_f32 v163, v110, v111
	v_add_u32_e32 v153, 0x10000, v164
	global_store_dwordx2 v153, v[162:163], s[38:39]
	global_store_dwordx4 v[228:229], v[100:103], off offset:64 sc1
	v_fmac_f32_e32 v171, v100, v100
	v_fmac_f32_e32 v171, v101, v101
	v_fmac_f32_e32 v171, v102, v102
	v_fmac_f32_e32 v171, v103, v103
	v_cvt_pk_bf16_f32 v162, v100, v101
	v_cvt_pk_bf16_f32 v163, v102, v103
	v_add_u32_e32 v153, 0x10000, v164
	global_store_dwordx2 v153, v[162:163], s[38:39] offset:32
	global_store_dwordx4 v[228:229], v[76:79], off offset:512 sc1
	v_fmac_f32_e32 v171, v76, v76
	v_fmac_f32_e32 v171, v77, v77
	v_fmac_f32_e32 v171, v78, v78
	v_fmac_f32_e32 v171, v79, v79
	v_cvt_pk_bf16_f32 v162, v76, v77
	v_cvt_pk_bf16_f32 v163, v78, v79
	v_add_u32_e32 v153, 0x10000, v164
	global_store_dwordx2 v153, v[162:163], s[38:39] offset:256
	global_store_dwordx4 v[228:229], v[72:75], off offset:576 sc1
	v_fmac_f32_e32 v171, v72, v72
	v_fmac_f32_e32 v171, v73, v73
	v_fmac_f32_e32 v171, v74, v74
	v_fmac_f32_e32 v171, v75, v75
	v_cvt_pk_bf16_f32 v162, v72, v73
	v_cvt_pk_bf16_f32 v163, v74, v75
	v_add_u32_e32 v153, 0x10000, v164
	global_store_dwordx2 v153, v[162:163], s[38:39] offset:288
	v_mov_b32_e32 v168, v171
	s_nop 1
	v_permlane16_swap_b32_e32 v168, v171
	v_add_f32_e32 v171, v168, v171
	v_mov_b32_e32 v168, v171
	s_nop 1
	v_permlane32_swap_b32_e32 v168, v171
	v_add_f32_e32 v171, v168, v171
	v_add_u32_e32 v153, 0x800, v165
	global_store_dword v153, v171, s[38:39]
	global_store_dwordx4 v[230:231], v[92:95], off sc1
	v_mul_f32_e32 v172, v92, v92
	v_fmac_f32_e32 v172, v93, v93
	v_fmac_f32_e32 v172, v94, v94
	v_fmac_f32_e32 v172, v95, v95
	v_cvt_pk_bf16_f32 v162, v92, v93
	v_cvt_pk_bf16_f32 v163, v94, v95
	v_add_u32_e32 v153, 0x18000, v164
	global_store_dwordx2 v153, v[162:163], s[38:39]
	global_store_dwordx4 v[230:231], v[80:83], off offset:64 sc1
	v_fmac_f32_e32 v172, v80, v80
	v_fmac_f32_e32 v172, v81, v81
	v_fmac_f32_e32 v172, v82, v82
	v_fmac_f32_e32 v172, v83, v83
	v_cvt_pk_bf16_f32 v162, v80, v81
	v_cvt_pk_bf16_f32 v163, v82, v83
	v_add_u32_e32 v153, 0x18000, v164
	global_store_dwordx2 v153, v[162:163], s[38:39] offset:32
	global_store_dwordx4 v[230:231], v[64:67], off offset:576 sc1
	v_fmac_f32_e32 v172, v64, v64
	v_fmac_f32_e32 v172, v65, v65
	v_fmac_f32_e32 v172, v66, v66
	v_fmac_f32_e32 v172, v67, v67
	v_cvt_pk_bf16_f32 v162, v64, v65
	v_cvt_pk_bf16_f32 v163, v66, v67
	v_add_u32_e32 v153, 0x18000, v164
	global_store_dwordx2 v153, v[162:163], s[38:39] offset:288
	v_add_u32_e32 v96, 0xa0, v144
	v_add_u32_e32 v80, 0x90, v144
	v_add_u32_e32 v64, 0x80, v144
	v_ashrrev_i32_e32 v65, 31, v64
	v_ashrrev_i32_e32 v81, 31, v80
	v_ashrrev_i32_e32 v97, 31, v96
	v_add_u32_e32 v112, 0xb0, v144
	v_pk_add_f32 v[70:71], v[70:71], v[220:221]
	v_pk_add_f32 v[68:69], v[68:69], v[218:219]
	v_lshlrev_b64 v[154:155], 12, v[64:65]
	v_lshlrev_b64 v[156:157], 12, v[80:81]
	v_lshlrev_b64 v[158:159], 12, v[96:97]
	v_ashrrev_i32_e32 v113, 31, v112
	global_store_dwordx4 v[230:231], v[68:71], off offset:512 sc1
	v_fmac_f32_e32 v172, v68, v68
	v_fmac_f32_e32 v172, v69, v69
	v_fmac_f32_e32 v172, v70, v70
	v_fmac_f32_e32 v172, v71, v71
	v_cvt_pk_bf16_f32 v162, v68, v69
	v_cvt_pk_bf16_f32 v163, v70, v71
	v_add_u32_e32 v153, 0x18000, v164
	global_store_dwordx2 v153, v[162:163], s[38:39] offset:256
	v_mov_b32_e32 v168, v172
	s_nop 1
	v_permlane16_swap_b32_e32 v168, v172
	v_add_f32_e32 v172, v168, v172
	v_mov_b32_e32 v168, v172
	s_nop 1
	v_permlane32_swap_b32_e32 v168, v172
	v_add_f32_e32 v172, v168, v172
	v_add_u32_e32 v153, 0xc00, v165
	global_store_dword v153, v172, s[38:39]
	v_lshl_add_u64 v[76:77], v[142:143], 0, v[154:155]
	v_lshl_add_u64 v[92:93], v[142:143], 0, v[156:157]
	v_lshl_add_u64 v[108:109], v[142:143], 0, v[158:159]
	v_lshlrev_b64 v[144:145], 12, v[112:113]
	global_load_dwordx4 v[64:67], v[76:77], off
	global_load_dwordx4 v[68:71], v[76:77], off offset:64
	global_load_dwordx4 v[72:75], v[76:77], off offset:512
	s_nop 0
	global_load_dwordx4 v[76:79], v[76:77], off offset:576
	s_nop 0
	global_load_dwordx4 v[80:83], v[92:93], off
	global_load_dwordx4 v[84:87], v[92:93], off offset:64
	global_load_dwordx4 v[88:91], v[92:93], off offset:512
	s_nop 0
	global_load_dwordx4 v[92:95], v[92:93], off offset:576
	s_nop 0
	global_load_dwordx4 v[96:99], v[108:109], off
	global_load_dwordx4 v[100:103], v[108:109], off offset:64
	global_load_dwordx4 v[104:107], v[108:109], off offset:512
	s_nop 0
	global_load_dwordx4 v[108:111], v[108:109], off offset:576
	v_lshl_add_u64 v[124:125], v[142:143], 0, v[144:145]
	global_load_dwordx4 v[112:115], v[124:125], off
	global_load_dwordx4 v[116:119], v[124:125], off offset:64
	global_load_dwordx4 v[120:123], v[124:125], off offset:512
	s_nop 0
	global_load_dwordx4 v[124:127], v[124:125], off offset:576
	v_lshl_add_u64 v[142:143], s[36:37], 0, v[154:155]
	v_lshl_add_u64 v[154:155], s[36:37], 0, v[156:157]
	v_lshl_add_u64 v[156:157], s[36:37], 0, v[158:159]
	v_lshl_add_u64 v[144:145], s[36:37], 0, v[144:145]
	v_lshl_add_u64 v[142:143], v[142:143], 0, v[140:141]
	v_lshl_add_u64 v[154:155], v[154:155], 0, v[140:141]
	v_lshl_add_u64 v[156:157], v[156:157], 0, v[140:141]
	s_waitcnt vmcnt(15)
	v_pk_add_f32 v[62:63], v[62:63], v[66:67]
	v_pk_add_f32 v[60:61], v[60:61], v[64:65]
	s_waitcnt vmcnt(14)
	v_pk_add_f32 v[58:59], v[58:59], v[70:71]
	v_pk_add_f32 v[56:57], v[56:57], v[68:69]
	s_waitcnt vmcnt(13)
	v_pk_add_f32 v[42:43], v[42:43], v[74:75]
	s_waitcnt vmcnt(4)
	v_pk_add_f32 v[12:13], v[12:13], v[108:109]
	v_pk_add_f32 v[40:41], v[40:41], v[72:73]
	v_pk_add_f32 v[34:35], v[34:35], v[78:79]
	v_pk_add_f32 v[32:33], v[32:33], v[76:77]
	v_pk_add_f32 v[54:55], v[54:55], v[82:83]
	v_pk_add_f32 v[52:53], v[52:53], v[80:81]
	v_pk_add_f32 v[50:51], v[50:51], v[86:87]
	v_pk_add_f32 v[48:49], v[48:49], v[84:85]
	v_pk_add_f32 v[26:27], v[26:27], v[90:91]
	v_pk_add_f32 v[24:25], v[24:25], v[88:89]
	v_pk_add_f32 v[22:23], v[22:23], v[94:95]
	v_pk_add_f32 v[20:21], v[20:21], v[92:93]
	v_pk_add_f32 v[46:47], v[46:47], v[98:99]
	v_pk_add_f32 v[44:45], v[44:45], v[96:97]
	v_pk_add_f32 v[38:39], v[38:39], v[102:103]
	v_pk_add_f32 v[36:37], v[36:37], v[100:101]
	v_pk_add_f32 v[18:19], v[18:19], v[106:107]
	v_pk_add_f32 v[16:17], v[16:17], v[104:105]
	v_pk_add_f32 v[14:15], v[14:15], v[110:111]
	s_waitcnt vmcnt(3)
	v_pk_add_f32 v[30:31], v[30:31], v[114:115]
	v_pk_add_f32 v[28:29], v[28:29], v[112:113]
	global_store_dwordx4 v[142:143], v[60:63], off sc1
	v_mul_f32_e32 v173, v60, v60
	v_fmac_f32_e32 v173, v61, v61
	v_fmac_f32_e32 v173, v62, v62
	v_fmac_f32_e32 v173, v63, v63
	v_cvt_pk_bf16_f32 v162, v60, v61
	v_cvt_pk_bf16_f32 v163, v62, v63
	v_add_u32_e32 v153, 0x40000, v164
	global_store_dwordx2 v153, v[162:163], s[38:39]
	global_store_dwordx4 v[142:143], v[56:59], off offset:64 sc1
	v_fmac_f32_e32 v173, v56, v56
	v_fmac_f32_e32 v173, v57, v57
	v_fmac_f32_e32 v173, v58, v58
	v_fmac_f32_e32 v173, v59, v59
	v_cvt_pk_bf16_f32 v162, v56, v57
	v_cvt_pk_bf16_f32 v163, v58, v59
	v_add_u32_e32 v153, 0x40000, v164
	global_store_dwordx2 v153, v[162:163], s[38:39] offset:32
	global_store_dwordx4 v[142:143], v[40:43], off offset:512 sc1
	v_fmac_f32_e32 v173, v40, v40
	v_fmac_f32_e32 v173, v41, v41
	v_fmac_f32_e32 v173, v42, v42
	v_fmac_f32_e32 v173, v43, v43
	v_cvt_pk_bf16_f32 v162, v40, v41
	v_cvt_pk_bf16_f32 v163, v42, v43
	v_add_u32_e32 v153, 0x40000, v164
	global_store_dwordx2 v153, v[162:163], s[38:39] offset:256
	global_store_dwordx4 v[142:143], v[32:35], off offset:576 sc1
	v_fmac_f32_e32 v173, v32, v32
	v_fmac_f32_e32 v173, v33, v33
	v_fmac_f32_e32 v173, v34, v34
	v_fmac_f32_e32 v173, v35, v35
	v_cvt_pk_bf16_f32 v162, v32, v33
	v_cvt_pk_bf16_f32 v163, v34, v35
	v_add_u32_e32 v153, 0x40000, v164
	global_store_dwordx2 v153, v[162:163], s[38:39] offset:288
	v_mov_b32_e32 v168, v173
	s_nop 1
	v_permlane16_swap_b32_e32 v168, v173
	v_add_f32_e32 v173, v168, v173
	v_mov_b32_e32 v168, v173
	s_nop 1
	v_permlane32_swap_b32_e32 v168, v173
	v_add_f32_e32 v173, v168, v173
	v_add_u32_e32 v153, 0x2000, v165
	global_store_dword v153, v173, s[38:39]
	global_store_dwordx4 v[154:155], v[52:55], off sc1
	v_mul_f32_e32 v174, v52, v52
	v_fmac_f32_e32 v174, v53, v53
	v_fmac_f32_e32 v174, v54, v54
	v_fmac_f32_e32 v174, v55, v55
	v_cvt_pk_bf16_f32 v162, v52, v53
	v_cvt_pk_bf16_f32 v163, v54, v55
	v_add_u32_e32 v153, 0x48000, v164
	global_store_dwordx2 v153, v[162:163], s[38:39]
	global_store_dwordx4 v[154:155], v[48:51], off offset:64 sc1
	v_fmac_f32_e32 v174, v48, v48
	v_fmac_f32_e32 v174, v49, v49
	v_fmac_f32_e32 v174, v50, v50
	v_fmac_f32_e32 v174, v51, v51
	v_cvt_pk_bf16_f32 v162, v48, v49
	v_cvt_pk_bf16_f32 v163, v50, v51
	v_add_u32_e32 v153, 0x48000, v164
	global_store_dwordx2 v153, v[162:163], s[38:39] offset:32
	global_store_dwordx4 v[154:155], v[24:27], off offset:512 sc1
	v_fmac_f32_e32 v174, v24, v24
	v_fmac_f32_e32 v174, v25, v25
	v_fmac_f32_e32 v174, v26, v26
	v_fmac_f32_e32 v174, v27, v27
	v_cvt_pk_bf16_f32 v162, v24, v25
	v_cvt_pk_bf16_f32 v163, v26, v27
	v_add_u32_e32 v153, 0x48000, v164
	global_store_dwordx2 v153, v[162:163], s[38:39] offset:256
	global_store_dwordx4 v[154:155], v[20:23], off offset:576 sc1
	v_fmac_f32_e32 v174, v20, v20
	v_fmac_f32_e32 v174, v21, v21
	v_fmac_f32_e32 v174, v22, v22
	v_fmac_f32_e32 v174, v23, v23
	v_cvt_pk_bf16_f32 v162, v20, v21
	v_cvt_pk_bf16_f32 v163, v22, v23
	v_add_u32_e32 v153, 0x48000, v164
	global_store_dwordx2 v153, v[162:163], s[38:39] offset:288
	v_mov_b32_e32 v168, v174
	s_nop 1
	v_permlane16_swap_b32_e32 v168, v174
	v_add_f32_e32 v174, v168, v174
	v_mov_b32_e32 v168, v174
	s_nop 1
	v_permlane32_swap_b32_e32 v168, v174
	v_add_f32_e32 v174, v168, v174
	v_add_u32_e32 v153, 0x2400, v165
	global_store_dword v153, v174, s[38:39]
	global_store_dwordx4 v[156:157], v[44:47], off sc1
	v_mul_f32_e32 v175, v44, v44
	v_fmac_f32_e32 v175, v45, v45
	v_fmac_f32_e32 v175, v46, v46
	v_fmac_f32_e32 v175, v47, v47
	v_cvt_pk_bf16_f32 v162, v44, v45
	v_cvt_pk_bf16_f32 v163, v46, v47
	v_add_u32_e32 v153, 0x50000, v164
	global_store_dwordx2 v153, v[162:163], s[38:39]
	global_store_dwordx4 v[156:157], v[36:39], off offset:64 sc1
	v_fmac_f32_e32 v175, v36, v36
	v_fmac_f32_e32 v175, v37, v37
	v_fmac_f32_e32 v175, v38, v38
	v_fmac_f32_e32 v175, v39, v39
	v_cvt_pk_bf16_f32 v162, v36, v37
	v_cvt_pk_bf16_f32 v163, v38, v39
	v_add_u32_e32 v153, 0x50000, v164
	global_store_dwordx2 v153, v[162:163], s[38:39] offset:32
	global_store_dwordx4 v[156:157], v[16:19], off offset:512 sc1
	v_fmac_f32_e32 v175, v16, v16
	v_fmac_f32_e32 v175, v17, v17
	v_fmac_f32_e32 v175, v18, v18
	v_fmac_f32_e32 v175, v19, v19
	v_cvt_pk_bf16_f32 v162, v16, v17
	v_cvt_pk_bf16_f32 v163, v18, v19
	v_add_u32_e32 v153, 0x50000, v164
	global_store_dwordx2 v153, v[162:163], s[38:39] offset:256
	global_store_dwordx4 v[156:157], v[12:15], off offset:576 sc1
	v_fmac_f32_e32 v175, v12, v12
	v_fmac_f32_e32 v175, v13, v13
	v_fmac_f32_e32 v175, v14, v14
	v_fmac_f32_e32 v175, v15, v15
	v_cvt_pk_bf16_f32 v162, v12, v13
	v_cvt_pk_bf16_f32 v163, v14, v15
	v_add_u32_e32 v153, 0x50000, v164
	global_store_dwordx2 v153, v[162:163], s[38:39] offset:288
	v_mov_b32_e32 v168, v175
	s_nop 1
	v_permlane16_swap_b32_e32 v168, v175
	v_add_f32_e32 v175, v168, v175
	v_mov_b32_e32 v168, v175
	s_nop 1
	v_permlane32_swap_b32_e32 v168, v175
	v_add_f32_e32 v175, v168, v175
	v_add_u32_e32 v153, 0x2800, v165
	global_store_dword v153, v175, s[38:39]
	s_waitcnt vmcnt(29)
	v_pk_add_f32 v[10:11], v[10:11], v[118:119]
	v_pk_add_f32 v[8:9], v[8:9], v[116:117]
	v_lshl_add_u64 v[12:13], v[144:145], 0, v[140:141]
	s_waitcnt vmcnt(28)
	v_pk_add_f32 v[6:7], v[6:7], v[122:123]
	v_pk_add_f32 v[4:5], v[4:5], v[120:121]
	s_waitcnt vmcnt(27)
	v_pk_add_f32 v[2:3], v[2:3], v[126:127]
	v_pk_add_f32 v[0:1], v[0:1], v[124:125]
	global_store_dwordx4 v[12:13], v[28:31], off sc1
	v_mul_f32_e32 v176, v28, v28
	v_fmac_f32_e32 v176, v29, v29
	v_fmac_f32_e32 v176, v30, v30
	v_fmac_f32_e32 v176, v31, v31
	v_cvt_pk_bf16_f32 v162, v28, v29
	v_cvt_pk_bf16_f32 v163, v30, v31
	v_add_u32_e32 v153, 0x58000, v164
	global_store_dwordx2 v153, v[162:163], s[38:39]
	global_store_dwordx4 v[12:13], v[8:11], off offset:64 sc1
	v_fmac_f32_e32 v176, v8, v8
	v_fmac_f32_e32 v176, v9, v9
	v_fmac_f32_e32 v176, v10, v10
	v_fmac_f32_e32 v176, v11, v11
	v_cvt_pk_bf16_f32 v162, v8, v9
	v_cvt_pk_bf16_f32 v163, v10, v11
	v_add_u32_e32 v153, 0x58000, v164
	global_store_dwordx2 v153, v[162:163], s[38:39] offset:32
	global_store_dwordx4 v[12:13], v[4:7], off offset:512 sc1
	v_fmac_f32_e32 v176, v4, v4
	v_fmac_f32_e32 v176, v5, v5
	v_fmac_f32_e32 v176, v6, v6
	v_fmac_f32_e32 v176, v7, v7
	v_cvt_pk_bf16_f32 v162, v4, v5
	v_cvt_pk_bf16_f32 v163, v6, v7
	v_add_u32_e32 v153, 0x58000, v164
	global_store_dwordx2 v153, v[162:163], s[38:39] offset:256
	global_store_dwordx4 v[12:13], v[0:3], off offset:576 sc1
	v_fmac_f32_e32 v176, v0, v0
	v_fmac_f32_e32 v176, v1, v1
	v_fmac_f32_e32 v176, v2, v2
	v_fmac_f32_e32 v176, v3, v3
	v_cvt_pk_bf16_f32 v162, v0, v1
	v_cvt_pk_bf16_f32 v163, v2, v3
	v_add_u32_e32 v153, 0x58000, v164
	global_store_dwordx2 v153, v[162:163], s[38:39] offset:288
	v_mov_b32_e32 v168, v176
	s_nop 1
	v_permlane16_swap_b32_e32 v168, v176
	v_add_f32_e32 v176, v168, v176
	v_mov_b32_e32 v168, v176
	s_nop 1
	v_permlane32_swap_b32_e32 v168, v176
	v_add_f32_e32 v176, v168, v176
	v_add_u32_e32 v153, 0x2c00, v165
	global_store_dword v153, v176, s[38:39]
	s_cbranch_vccnz .LBB0_414
	s_andn2_b64 vcc, exec, s[8:9]
	s_cbranch_vccnz .LBB0_413
	s_barrier
	s_branch .LBB0_413

.LBB0_481:
	s_or_b64 exec, exec, s[4:5]
	s_waitcnt lgkmcnt(0)
	v_mov_b32_e32 v0, v160
	s_barrier
	s_nop 0
	v_readfirstlane_b32 s0, v0
	s_ashr_i32 s0, s0, 6
	s_add_i32 s4, s0, s91
	s_cmpk_gt_i32 s4, 0x3fff
	s_branch .LBB0_486
	s_load_dwordx2 s[0:1], s[92:93], 0x38
	v_and_b32_e32 v34, 63, v0
	v_lshlrev_b32_e32 v32, 4, v34
	s_ashr_i32 s5, s4, 31
	v_and_b32_e32 v35, 64, v211
	s_waitcnt lgkmcnt(0)
	global_load_dwordx4 v[0:3], v32, s[0:1]
	global_load_dwordx4 v[4:7], v32, s[0:1] offset:1024
	global_load_dwordx4 v[8:11], v32, s[0:1] offset:2048
	global_load_dwordx4 v[12:15], v32, s[0:1] offset:3072
	s_lshl_b64 s[0:1], s[4:5], 12
	s_add_u32 s0, s36, s0
	s_addc_u32 s1, s37, s1
	global_load_dwordx4 v[28:31], v32, s[0:1]
	global_load_dwordx4 v[24:27], v32, s[0:1] offset:1024
	global_load_dwordx4 v[20:23], v32, s[0:1] offset:2048
	global_load_dwordx4 v[16:19], v32, s[0:1] offset:3072
	v_add_u32_e32 v35, 64, v35
	v_xor_b32_e32 v36, 1, v211
	v_cmp_lt_i32_e32 vcc, v36, v35
	s_lshl_b64 s[0:1], s[4:5], 11
	v_mov_b32_e32 v33, 0
	v_cndmask_b32_e32 v36, v211, v36, vcc
	v_lshlrev_b32_e32 v52, 2, v36
	v_xor_b32_e32 v36, 2, v211
	v_cmp_lt_i32_e32 vcc, v36, v35
	s_add_u32 s0, s38, s0
	v_lshlrev_b32_e32 v34, 3, v34
	v_cndmask_b32_e32 v36, v211, v36, vcc
	v_lshlrev_b32_e32 v53, 2, v36
	v_xor_b32_e32 v36, 4, v211
	v_cmp_lt_i32_e32 vcc, v36, v35
	s_addc_u32 s1, s39, s1
	s_ashr_i32 s35, s34, 31
	v_cndmask_b32_e32 v36, v211, v36, vcc
	v_lshlrev_b32_e32 v54, 2, v36
	v_xor_b32_e32 v36, 8, v211
	v_cmp_lt_i32_e32 vcc, v36, v35
	s_lshl_b64 s[8:9], s[34:35], 11
	v_mov_b32_e32 v58, 0x358637bd
	v_cndmask_b32_e32 v36, v211, v36, vcc
	v_lshlrev_b32_e32 v55, 2, v36
	v_xor_b32_e32 v36, 16, v211
	v_cmp_lt_i32_e32 vcc, v36, v35
	s_nop 1
	v_cndmask_b32_e32 v36, v211, v36, vcc
	v_lshlrev_b32_e32 v56, 2, v36
	v_xor_b32_e32 v36, 32, v211
	v_cmp_lt_i32_e32 vcc, v36, v35
	s_nop 1
	v_cndmask_b32_e32 v35, v211, v36, vcc
	v_lshlrev_b32_e32 v57, 2, v35
	v_mov_b32_e32 v35, v33
	v_lshl_add_u64 v[34:35], s[0:1], 0, v[34:35]
	s_mov_b64 s[0:1], 0x8000000
	v_lshl_add_u64 v[48:49], v[34:35], 0, s[0:1]
	s_add_i32 s0, s4, s34
	s_ashr_i32 s1, s0, 31
	s_lshl_b64 s[0:1], s[0:1], 12
	s_add_u32 s0, s36, s0
	s_addc_u32 s1, s37, s1
	v_lshl_add_u64 v[50:51], s[0:1], 0, v[32:33]
	s_lshl_b64 s[10:11], s[34:35], 12
	s_mov_b32 s0, 0x800000
	s_branch .LBB0_484

.LBB0_558:
	v_lshl_add_u32 v153, s24, 8, v146
	v_and_b32_e32 v165, 48, v160
	v_lshl_add_u32 v153, v153, 6, v165
	v_add_u32_e32 v153, 0xc200000, v153
	v_add_u32_e32 v164, 0x2000, v153
	v_mov_b32_e32 v192, 0x358637bd
	global_load_dwordx4 v[168:171], v153, s[38:39]
	global_load_dwordx4 v[172:175], v153, s[38:39] offset:1024
	global_load_dwordx4 v[176:179], v153, s[38:39] offset:2048
	global_load_dwordx4 v[180:183], v153, s[38:39] offset:3072
	global_load_dwordx4 v[184:187], v164, s[38:39]
	global_load_dwordx4 v[188:191], v164, s[38:39] offset:1024
	global_load_dwordx4 v[200:203], v164, s[38:39] offset:2048
	global_load_dwordx4 v[204:207], v164, s[38:39] offset:3072
	s_waitcnt vmcnt(0)
	v_add_f32_e32 v168, v168, v169
	v_add_f32_e32 v170, v170, v171
	v_add_f32_e32 v168, v168, v170
	v_mov_b32_e32 v165, v168
	s_nop 1
	v_permlane16_swap_b32_e32 v165, v168
	v_add_f32_e32 v168, v165, v168
	v_mov_b32_e32 v165, v168
	s_nop 1
	v_permlane32_swap_b32_e32 v165, v168
	v_add_f32_e32 v168, v165, v168
	v_fmamk_f32 v168, v168, 0x3a800000, v192
	v_rsq_f32_e32 v168, v168
	s_nop 0
	v_add_f32_e32 v172, v172, v173
	v_add_f32_e32 v174, v174, v175
	v_add_f32_e32 v172, v172, v174
	v_mov_b32_e32 v165, v172
	s_nop 1
	v_permlane16_swap_b32_e32 v165, v172
	v_add_f32_e32 v172, v165, v172
	v_mov_b32_e32 v165, v172
	s_nop 1
	v_permlane32_swap_b32_e32 v165, v172
	v_add_f32_e32 v172, v165, v172
	v_fmamk_f32 v172, v172, 0x3a800000, v192
	v_rsq_f32_e32 v172, v172
	s_nop 0
	v_add_f32_e32 v176, v176, v177
	v_add_f32_e32 v178, v178, v179
	v_add_f32_e32 v176, v176, v178
	v_mov_b32_e32 v165, v176
	s_nop 1
	v_permlane16_swap_b32_e32 v165, v176
	v_add_f32_e32 v176, v165, v176
	v_mov_b32_e32 v165, v176
	s_nop 1
	v_permlane32_swap_b32_e32 v165, v176
	v_add_f32_e32 v176, v165, v176
	v_fmamk_f32 v176, v176, 0x3a800000, v192
	v_rsq_f32_e32 v176, v176
	s_nop 0
	v_add_f32_e32 v180, v180, v181
	v_add_f32_e32 v182, v182, v183
	v_add_f32_e32 v180, v180, v182
	v_mov_b32_e32 v165, v180
	s_nop 1
	v_permlane16_swap_b32_e32 v165, v180
	v_add_f32_e32 v180, v165, v180
	v_mov_b32_e32 v165, v180
	s_nop 1
	v_permlane32_swap_b32_e32 v165, v180
	v_add_f32_e32 v180, v165, v180
	v_fmamk_f32 v180, v180, 0x3a800000, v192
	v_rsq_f32_e32 v180, v180
	s_nop 0
	v_add_f32_e32 v184, v184, v185
	v_add_f32_e32 v186, v186, v187
	v_add_f32_e32 v184, v184, v186
	v_mov_b32_e32 v165, v184
	s_nop 1
	v_permlane16_swap_b32_e32 v165, v184
	v_add_f32_e32 v184, v165, v184
	v_mov_b32_e32 v165, v184
	s_nop 1
	v_permlane32_swap_b32_e32 v165, v184
	v_add_f32_e32 v184, v165, v184
	v_fmamk_f32 v184, v184, 0x3a800000, v192
	v_rsq_f32_e32 v184, v184
	s_nop 0
	v_add_f32_e32 v188, v188, v189
	v_add_f32_e32 v190, v190, v191
	v_add_f32_e32 v188, v188, v190
	v_mov_b32_e32 v165, v188
	s_nop 1
	v_permlane16_swap_b32_e32 v165, v188
	v_add_f32_e32 v188, v165, v188
	v_mov_b32_e32 v165, v188
	s_nop 1
	v_permlane32_swap_b32_e32 v165, v188
	v_add_f32_e32 v188, v165, v188
	v_fmamk_f32 v188, v188, 0x3a800000, v192
	v_rsq_f32_e32 v188, v188
	s_nop 0
	v_add_f32_e32 v200, v200, v201
	v_add_f32_e32 v202, v202, v203
	v_add_f32_e32 v200, v200, v202
	v_mov_b32_e32 v165, v200
	s_nop 1
	v_permlane16_swap_b32_e32 v165, v200
	v_add_f32_e32 v200, v165, v200
	v_mov_b32_e32 v165, v200
	s_nop 1
	v_permlane32_swap_b32_e32 v165, v200
	v_add_f32_e32 v200, v165, v200
	v_fmamk_f32 v200, v200, 0x3a800000, v192
	v_rsq_f32_e32 v200, v200
	s_nop 0
	v_add_f32_e32 v204, v204, v205
	v_add_f32_e32 v206, v206, v207
	v_add_f32_e32 v204, v204, v206
	v_mov_b32_e32 v165, v204
	s_nop 1
	v_permlane16_swap_b32_e32 v165, v204
	v_add_f32_e32 v204, v165, v204
	v_mov_b32_e32 v165, v204
	s_nop 1
	v_permlane32_swap_b32_e32 v165, v204
	v_add_f32_e32 v204, v165, v204
	v_fmamk_f32 v204, v204, 0x3a800000, v192
	v_rsq_f32_e32 v204, v204
	s_nop 0
	v_mul_f32_e32 v112, v112, v168
	v_mul_f32_e32 v113, v113, v168
	v_mul_f32_e32 v114, v114, v168
	v_mul_f32_e32 v115, v115, v168
	v_mul_f32_e32 v116, v116, v168
	v_mul_f32_e32 v117, v117, v168
	v_mul_f32_e32 v118, v118, v168
	v_mul_f32_e32 v119, v119, v168
	v_mul_f32_e32 v120, v120, v168
	v_mul_f32_e32 v121, v121, v168
	v_mul_f32_e32 v122, v122, v168
	v_mul_f32_e32 v123, v123, v168
	v_mul_f32_e32 v124, v124, v168
	v_mul_f32_e32 v125, v125, v168
	v_mul_f32_e32 v126, v126, v168
	v_mul_f32_e32 v127, v127, v168
	v_mul_f32_e32 v96, v96, v172
	v_mul_f32_e32 v97, v97, v172
	v_mul_f32_e32 v98, v98, v172
	v_mul_f32_e32 v99, v99, v172
	v_mul_f32_e32 v100, v100, v172
	v_mul_f32_e32 v101, v101, v172
	v_mul_f32_e32 v102, v102, v172
	v_mul_f32_e32 v103, v103, v172
	v_mul_f32_e32 v104, v104, v172
	v_mul_f32_e32 v105, v105, v172
	v_mul_f32_e32 v106, v106, v172
	v_mul_f32_e32 v107, v107, v172
	v_mul_f32_e32 v108, v108, v172
	v_mul_f32_e32 v109, v109, v172
	v_mul_f32_e32 v110, v110, v172
	v_mul_f32_e32 v111, v111, v172
	v_mul_f32_e32 v80, v80, v176
	v_mul_f32_e32 v81, v81, v176
	v_mul_f32_e32 v82, v82, v176
	v_mul_f32_e32 v83, v83, v176
	v_mul_f32_e32 v84, v84, v176
	v_mul_f32_e32 v85, v85, v176
	v_mul_f32_e32 v86, v86, v176
	v_mul_f32_e32 v87, v87, v176
	v_mul_f32_e32 v88, v88, v176
	v_mul_f32_e32 v89, v89, v176
	v_mul_f32_e32 v90, v90, v176
	v_mul_f32_e32 v91, v91, v176
	v_mul_f32_e32 v92, v92, v176
	v_mul_f32_e32 v93, v93, v176
	v_mul_f32_e32 v94, v94, v176
	v_mul_f32_e32 v95, v95, v176
	v_mul_f32_e32 v64, v64, v180
	v_mul_f32_e32 v65, v65, v180
	v_mul_f32_e32 v66, v66, v180
	v_mul_f32_e32 v67, v67, v180
	v_mul_f32_e32 v68, v68, v180
	v_mul_f32_e32 v69, v69, v180
	v_mul_f32_e32 v70, v70, v180
	v_mul_f32_e32 v71, v71, v180
	v_mul_f32_e32 v72, v72, v180
	v_mul_f32_e32 v73, v73, v180
	v_mul_f32_e32 v74, v74, v180
	v_mul_f32_e32 v75, v75, v180
	v_mul_f32_e32 v76, v76, v180
	v_mul_f32_e32 v77, v77, v180
	v_mul_f32_e32 v78, v78, v180
	v_mul_f32_e32 v79, v79, v180
	v_mul_f32_e32 v48, v48, v184
	v_mul_f32_e32 v49, v49, v184
	v_mul_f32_e32 v50, v50, v184
	v_mul_f32_e32 v51, v51, v184
	v_mul_f32_e32 v52, v52, v184
	v_mul_f32_e32 v53, v53, v184
	v_mul_f32_e32 v54, v54, v184
	v_mul_f32_e32 v55, v55, v184
	v_mul_f32_e32 v56, v56, v184
	v_mul_f32_e32 v57, v57, v184
	v_mul_f32_e32 v58, v58, v184
	v_mul_f32_e32 v59, v59, v184
	v_mul_f32_e32 v60, v60, v184
	v_mul_f32_e32 v61, v61, v184
	v_mul_f32_e32 v62, v62, v184
	v_mul_f32_e32 v63, v63, v184
	v_mul_f32_e32 v32, v32, v188
	v_mul_f32_e32 v33, v33, v188
	v_mul_f32_e32 v34, v34, v188
	v_mul_f32_e32 v35, v35, v188
	v_mul_f32_e32 v36, v36, v188
	v_mul_f32_e32 v37, v37, v188
	v_mul_f32_e32 v38, v38, v188
	v_mul_f32_e32 v39, v39, v188
	v_mul_f32_e32 v40, v40, v188
	v_mul_f32_e32 v41, v41, v188
	v_mul_f32_e32 v42, v42, v188
	v_mul_f32_e32 v43, v43, v188
	v_mul_f32_e32 v44, v44, v188
	v_mul_f32_e32 v45, v45, v188
	v_mul_f32_e32 v46, v46, v188
	v_mul_f32_e32 v47, v47, v188
	v_mul_f32_e32 v16, v16, v200
	v_mul_f32_e32 v17, v17, v200
	v_mul_f32_e32 v18, v18, v200
	v_mul_f32_e32 v19, v19, v200
	v_mul_f32_e32 v20, v20, v200
	v_mul_f32_e32 v21, v21, v200
	v_mul_f32_e32 v22, v22, v200
	v_mul_f32_e32 v23, v23, v200
	v_mul_f32_e32 v24, v24, v200
	v_mul_f32_e32 v25, v25, v200
	v_mul_f32_e32 v26, v26, v200
	v_mul_f32_e32 v27, v27, v200
	v_mul_f32_e32 v28, v28, v200
	v_mul_f32_e32 v29, v29, v200
	v_mul_f32_e32 v30, v30, v200
	v_mul_f32_e32 v31, v31, v200
	v_mul_f32_e32 v0, v0, v204
	v_mul_f32_e32 v1, v1, v204
	v_mul_f32_e32 v2, v2, v204
	v_mul_f32_e32 v3, v3, v204
	v_mul_f32_e32 v4, v4, v204
	v_mul_f32_e32 v5, v5, v204
	v_mul_f32_e32 v6, v6, v204
	v_mul_f32_e32 v7, v7, v204
	v_mul_f32_e32 v8, v8, v204
	v_mul_f32_e32 v9, v9, v204
	v_mul_f32_e32 v10, v10, v204
	v_mul_f32_e32 v11, v11, v204
	v_mul_f32_e32 v12, v12, v204
	v_mul_f32_e32 v13, v13, v204
	v_mul_f32_e32 v14, v14, v204
	v_mul_f32_e32 v15, v15, v204
	v_lshl_add_u32 v154, s24, 8, v146
	v_lshl_or_b32 v144, s48, 8, v147
	v_ashrrev_i32_e32 v155, 31, v154
	v_ashrrev_i32_e32 v145, 31, v144
	v_lshlrev_b64 v[156:157], 13, v[154:155]
	v_max_f32_e32 v120, v120, v120
	v_max_f32_e32 v121, v121, v121
	v_lshl_add_u64 v[156:157], s[38:39], 0, v[156:157]
	v_lshlrev_b64 v[158:159], 1, v[144:145]
	v_max_f32_e32 v120, 0, v120
	v_max_f32_e32 v121, 0, v121
	v_lshl_add_u64 v[144:145], v[156:157], 0, v[158:159]
	v_pk_mul_f32 v[156:157], v[120:121], v[120:121]
	v_max_f32_e32 v121, v122, v122
	v_max_f32_e32 v124, v124, v124
	v_max_f32_e32 v125, v125, v125
	v_max_f32_e32 v120, v126, v126
	v_max_f32_e32 v122, 0, v121
	v_max_f32_e32 v121, v127, v127
	v_max_f32_e32 v123, v123, v123
	v_max_f32_e32 v124, 0, v124
	v_max_f32_e32 v125, 0, v125
	v_max_f32_e32 v120, 0, v120
	v_max_f32_e32 v121, 0, v121
	v_max_f32_e32 v123, 0, v123
	v_pk_mul_f32 v[124:125], v[124:125], v[124:125]
	v_pk_mul_f32 v[126:127], v[120:121], v[120:121]
	v_pk_mul_f32 v[162:163], v[122:123], v[122:123]
	v_max_f32_e32 v112, v112, v112
	v_max_f32_e32 v113, v113, v113
	v_cvt_pk_bf16_f32 v120, v124, v125
	v_cvt_pk_bf16_f32 v121, v126, v127
	v_cvt_pk_bf16_f32 v122, v156, v157
	v_cvt_pk_bf16_f32 v123, v162, v163
	v_max_f32_e32 v112, 0, v112
	v_max_f32_e32 v113, 0, v113
	global_store_dwordx4 v[144:145], v[120:123], off sc1
	v_max_f32_e32 v116, v116, v116
	v_max_f32_e32 v117, v117, v117
	v_pk_mul_f32 v[120:121], v[112:113], v[112:113]
	v_max_f32_e32 v113, v114, v114
	v_max_f32_e32 v112, v118, v118
	v_max_f32_e32 v114, 0, v113
	v_max_f32_e32 v113, v119, v119
	v_max_f32_e32 v115, v115, v115
	v_max_f32_e32 v116, 0, v116
	v_max_f32_e32 v117, 0, v117
	v_max_f32_e32 v112, 0, v112
	v_max_f32_e32 v113, 0, v113
	v_max_f32_e32 v115, 0, v115
	v_pk_mul_f32 v[116:117], v[116:117], v[116:117]
	v_pk_mul_f32 v[118:119], v[112:113], v[112:113]
	v_pk_mul_f32 v[122:123], v[114:115], v[114:115]
	v_max_f32_e32 v104, v104, v104
	v_max_f32_e32 v105, v105, v105
	v_cvt_pk_bf16_f32 v112, v116, v117
	v_cvt_pk_bf16_f32 v113, v118, v119
	v_cvt_pk_bf16_f32 v114, v120, v121
	v_cvt_pk_bf16_f32 v115, v122, v123
	v_max_f32_e32 v104, 0, v104
	v_max_f32_e32 v105, 0, v105
	global_store_dwordx4 v[144:145], v[112:115], off offset:256 sc1
	v_max_f32_e32 v108, v108, v108
	v_max_f32_e32 v109, v109, v109
	v_or_b32_e32 v112, 16, v154
	v_pk_mul_f32 v[114:115], v[104:105], v[104:105]
	v_max_f32_e32 v105, v106, v106
	v_ashrrev_i32_e32 v113, 31, v112
	v_max_f32_e32 v104, v110, v110
	v_max_f32_e32 v106, 0, v105
	v_max_f32_e32 v105, v111, v111
	v_max_f32_e32 v107, v107, v107
	v_lshlrev_b64 v[112:113], 13, v[112:113]
	v_max_f32_e32 v108, 0, v108
	v_max_f32_e32 v109, 0, v109
	v_max_f32_e32 v104, 0, v104
	v_max_f32_e32 v105, 0, v105
	v_max_f32_e32 v107, 0, v107
	v_lshl_add_u64 v[112:113], s[38:39], 0, v[112:113]
	v_pk_mul_f32 v[108:109], v[108:109], v[108:109]
	v_pk_mul_f32 v[110:111], v[104:105], v[104:105]
	v_pk_mul_f32 v[116:117], v[106:107], v[106:107]
	v_max_f32_e32 v96, v96, v96
	v_max_f32_e32 v97, v97, v97
	v_lshl_add_u64 v[112:113], v[112:113], 0, v[158:159]
	v_cvt_pk_bf16_f32 v104, v108, v109
	v_cvt_pk_bf16_f32 v105, v110, v111
	v_cvt_pk_bf16_f32 v106, v114, v115
	v_cvt_pk_bf16_f32 v107, v116, v117
	v_max_f32_e32 v96, 0, v96
	v_max_f32_e32 v97, 0, v97
	global_store_dwordx4 v[112:113], v[104:107], off sc1
	v_max_f32_e32 v100, v100, v100
	v_max_f32_e32 v101, v101, v101
	v_pk_mul_f32 v[104:105], v[96:97], v[96:97]
	v_max_f32_e32 v97, v98, v98
	v_max_f32_e32 v96, v102, v102
	v_max_f32_e32 v98, 0, v97
	v_max_f32_e32 v97, v103, v103
	v_max_f32_e32 v99, v99, v99
	v_max_f32_e32 v100, 0, v100
	v_max_f32_e32 v101, 0, v101
	v_max_f32_e32 v96, 0, v96
	v_max_f32_e32 v97, 0, v97
	v_max_f32_e32 v99, 0, v99
	v_pk_mul_f32 v[100:101], v[100:101], v[100:101]
	v_pk_mul_f32 v[102:103], v[96:97], v[96:97]
	v_pk_mul_f32 v[106:107], v[98:99], v[98:99]
	v_max_f32_e32 v88, v88, v88
	v_max_f32_e32 v89, v89, v89
	v_cvt_pk_bf16_f32 v96, v100, v101
	v_cvt_pk_bf16_f32 v97, v102, v103
	v_cvt_pk_bf16_f32 v98, v104, v105
	v_cvt_pk_bf16_f32 v99, v106, v107
	v_max_f32_e32 v88, 0, v88
	v_max_f32_e32 v89, 0, v89
	global_store_dwordx4 v[112:113], v[96:99], off offset:256 sc1
	v_max_f32_e32 v92, v92, v92
	v_max_f32_e32 v93, v93, v93
	v_or_b32_e32 v96, 32, v154
	v_pk_mul_f32 v[98:99], v[88:89], v[88:89]
	v_max_f32_e32 v89, v90, v90
	v_ashrrev_i32_e32 v97, 31, v96
	v_max_f32_e32 v88, v94, v94
	v_max_f32_e32 v90, 0, v89
	v_max_f32_e32 v89, v95, v95
	v_max_f32_e32 v91, v91, v91
	v_lshlrev_b64 v[96:97], 13, v[96:97]
	v_max_f32_e32 v92, 0, v92
	v_max_f32_e32 v93, 0, v93
	v_max_f32_e32 v88, 0, v88
	v_max_f32_e32 v89, 0, v89
	v_max_f32_e32 v91, 0, v91
	v_lshl_add_u64 v[96:97], s[38:39], 0, v[96:97]
	v_pk_mul_f32 v[92:93], v[92:93], v[92:93]
	v_pk_mul_f32 v[94:95], v[88:89], v[88:89]
	v_pk_mul_f32 v[100:101], v[90:91], v[90:91]
	v_max_f32_e32 v80, v80, v80
	v_max_f32_e32 v81, v81, v81
	v_lshl_add_u64 v[96:97], v[96:97], 0, v[158:159]
	v_cvt_pk_bf16_f32 v88, v92, v93
	v_cvt_pk_bf16_f32 v89, v94, v95
	v_cvt_pk_bf16_f32 v90, v98, v99
	v_cvt_pk_bf16_f32 v91, v100, v101
	v_max_f32_e32 v80, 0, v80
	v_max_f32_e32 v81, 0, v81
	global_store_dwordx4 v[96:97], v[88:91], off sc1
	v_max_f32_e32 v84, v84, v84
	v_max_f32_e32 v85, v85, v85
	v_pk_mul_f32 v[88:89], v[80:81], v[80:81]
	v_max_f32_e32 v81, v82, v82
	v_max_f32_e32 v80, v86, v86
	v_max_f32_e32 v82, 0, v81
	v_max_f32_e32 v81, v87, v87
	v_max_f32_e32 v83, v83, v83
	v_max_f32_e32 v84, 0, v84
	v_max_f32_e32 v85, 0, v85
	v_max_f32_e32 v80, 0, v80
	v_max_f32_e32 v81, 0, v81
	v_max_f32_e32 v83, 0, v83
	v_pk_mul_f32 v[84:85], v[84:85], v[84:85]
	v_pk_mul_f32 v[86:87], v[80:81], v[80:81]
	v_pk_mul_f32 v[90:91], v[82:83], v[82:83]
	v_max_f32_e32 v72, v72, v72
	v_max_f32_e32 v73, v73, v73
	v_cvt_pk_bf16_f32 v80, v84, v85
	v_cvt_pk_bf16_f32 v81, v86, v87
	v_cvt_pk_bf16_f32 v82, v88, v89
	v_cvt_pk_bf16_f32 v83, v90, v91
	v_max_f32_e32 v72, 0, v72
	v_max_f32_e32 v73, 0, v73
	global_store_dwordx4 v[96:97], v[80:83], off offset:256 sc1
	v_max_f32_e32 v76, v76, v76
	v_max_f32_e32 v77, v77, v77
	v_or_b32_e32 v80, 48, v154
	v_pk_mul_f32 v[82:83], v[72:73], v[72:73]
	v_max_f32_e32 v73, v74, v74
	v_ashrrev_i32_e32 v81, 31, v80
	v_max_f32_e32 v72, v78, v78
	v_max_f32_e32 v74, 0, v73
	v_max_f32_e32 v73, v79, v79
	v_max_f32_e32 v75, v75, v75
	v_lshlrev_b64 v[80:81], 13, v[80:81]
	v_max_f32_e32 v76, 0, v76
	v_max_f32_e32 v77, 0, v77
	v_max_f32_e32 v72, 0, v72
	v_max_f32_e32 v73, 0, v73
	v_max_f32_e32 v75, 0, v75
	v_lshl_add_u64 v[80:81], s[38:39], 0, v[80:81]
	v_pk_mul_f32 v[76:77], v[76:77], v[76:77]
	v_pk_mul_f32 v[78:79], v[72:73], v[72:73]
	v_pk_mul_f32 v[84:85], v[74:75], v[74:75]
	v_max_f32_e32 v64, v64, v64
	v_max_f32_e32 v65, v65, v65
	v_lshl_add_u64 v[80:81], v[80:81], 0, v[158:159]
	v_cvt_pk_bf16_f32 v72, v76, v77
	v_cvt_pk_bf16_f32 v73, v78, v79
	v_cvt_pk_bf16_f32 v74, v82, v83
	v_cvt_pk_bf16_f32 v75, v84, v85
	v_max_f32_e32 v64, 0, v64
	v_max_f32_e32 v65, 0, v65
	global_store_dwordx4 v[80:81], v[72:75], off sc1
	v_max_f32_e32 v68, v68, v68
	v_max_f32_e32 v69, v69, v69
	v_pk_mul_f32 v[72:73], v[64:65], v[64:65]
	v_max_f32_e32 v65, v66, v66
	v_max_f32_e32 v64, v70, v70
	v_max_f32_e32 v66, 0, v65
	v_max_f32_e32 v65, v71, v71
	v_max_f32_e32 v67, v67, v67
	v_max_f32_e32 v68, 0, v68
	v_max_f32_e32 v69, 0, v69
	v_max_f32_e32 v64, 0, v64
	v_max_f32_e32 v65, 0, v65
	v_max_f32_e32 v67, 0, v67
	v_pk_mul_f32 v[68:69], v[68:69], v[68:69]
	v_pk_mul_f32 v[70:71], v[64:65], v[64:65]
	v_pk_mul_f32 v[74:75], v[66:67], v[66:67]
	v_max_f32_e32 v56, v56, v56
	v_max_f32_e32 v57, v57, v57
	v_cvt_pk_bf16_f32 v64, v68, v69
	v_cvt_pk_bf16_f32 v65, v70, v71
	v_cvt_pk_bf16_f32 v66, v72, v73
	v_cvt_pk_bf16_f32 v67, v74, v75
	v_max_f32_e32 v56, 0, v56
	v_max_f32_e32 v57, 0, v57
	global_store_dwordx4 v[80:81], v[64:67], off offset:256 sc1
	v_max_f32_e32 v60, v60, v60
	v_max_f32_e32 v61, v61, v61
	v_pk_mul_f32 v[66:67], v[56:57], v[56:57]
	v_max_f32_e32 v57, v58, v58
	v_max_f32_e32 v60, 0, v60
	v_max_f32_e32 v61, 0, v61
	v_max_f32_e32 v56, v62, v62
	v_max_f32_e32 v58, 0, v57
	v_max_f32_e32 v57, v63, v63
	v_max_f32_e32 v59, v59, v59
	v_pk_mul_f32 v[60:61], v[60:61], v[60:61]
	v_max_f32_e32 v56, 0, v56
	v_max_f32_e32 v57, 0, v57
	v_max_f32_e32 v59, 0, v59
	s_mov_b32 s17, 0x100000
	v_pk_mul_f32 v[62:63], v[56:57], v[56:57]
	v_pk_mul_f32 v[68:69], v[58:59], v[58:59]
	v_cvt_pk_bf16_f32 v56, v60, v61
	v_add_co_u32_e32 v60, vcc, s17, v144
	v_max_f32_e32 v48, v48, v48
	v_max_f32_e32 v49, v49, v49
	v_cvt_pk_bf16_f32 v57, v62, v63
	v_cvt_pk_bf16_f32 v58, v66, v67
	v_cvt_pk_bf16_f32 v59, v68, v69
	v_addc_co_u32_e32 v61, vcc, 0, v145, vcc
	v_max_f32_e32 v48, 0, v48
	v_max_f32_e32 v49, 0, v49
	global_store_dwordx4 v[60:61], v[56:59], off sc1
	v_max_f32_e32 v52, v52, v52
	v_max_f32_e32 v53, v53, v53
	v_pk_mul_f32 v[56:57], v[48:49], v[48:49]
	v_max_f32_e32 v49, v50, v50
	v_max_f32_e32 v48, v54, v54
	v_max_f32_e32 v50, 0, v49
	v_max_f32_e32 v49, v55, v55
	v_max_f32_e32 v51, v51, v51
	v_max_f32_e32 v52, 0, v52
	v_max_f32_e32 v53, 0, v53
	v_max_f32_e32 v48, 0, v48
	v_max_f32_e32 v49, 0, v49
	v_max_f32_e32 v51, 0, v51
	s_mov_b64 s[48:49], 0x100000
	v_pk_mul_f32 v[52:53], v[52:53], v[52:53]
	v_pk_mul_f32 v[54:55], v[48:49], v[48:49]
	v_pk_mul_f32 v[58:59], v[50:51], v[50:51]
	v_max_f32_e32 v40, v40, v40
	v_max_f32_e32 v41, v41, v41
	v_lshl_add_u64 v[64:65], v[144:145], 0, s[48:49]
	v_cvt_pk_bf16_f32 v48, v52, v53
	v_cvt_pk_bf16_f32 v49, v54, v55
	v_cvt_pk_bf16_f32 v50, v56, v57
	v_cvt_pk_bf16_f32 v51, v58, v59
	v_max_f32_e32 v40, 0, v40
	v_max_f32_e32 v41, 0, v41
	global_store_dwordx4 v[64:65], v[48:51], off offset:256 sc1
	v_max_f32_e32 v44, v44, v44
	v_max_f32_e32 v45, v45, v45
	v_pk_mul_f32 v[50:51], v[40:41], v[40:41]
	v_max_f32_e32 v41, v42, v42
	v_max_f32_e32 v44, 0, v44
	v_max_f32_e32 v45, 0, v45
	v_max_f32_e32 v40, v46, v46
	v_max_f32_e32 v42, 0, v41
	v_max_f32_e32 v41, v47, v47
	v_max_f32_e32 v43, v43, v43
	v_pk_mul_f32 v[44:45], v[44:45], v[44:45]
	v_max_f32_e32 v40, 0, v40
	v_max_f32_e32 v41, 0, v41
	v_max_f32_e32 v43, 0, v43
	s_mov_b32 s17, 0x120000
	v_pk_mul_f32 v[46:47], v[40:41], v[40:41]
	v_pk_mul_f32 v[52:53], v[42:43], v[42:43]
	v_cvt_pk_bf16_f32 v40, v44, v45
	v_add_co_u32_e32 v44, vcc, s17, v144
	v_max_f32_e32 v32, v32, v32
	v_max_f32_e32 v33, v33, v33
	v_cvt_pk_bf16_f32 v41, v46, v47
	v_cvt_pk_bf16_f32 v42, v50, v51
	v_cvt_pk_bf16_f32 v43, v52, v53
	v_addc_co_u32_e32 v45, vcc, 0, v145, vcc
	v_max_f32_e32 v32, 0, v32
	v_max_f32_e32 v33, 0, v33
	global_store_dwordx4 v[44:45], v[40:43], off sc1
	v_max_f32_e32 v36, v36, v36
	v_max_f32_e32 v37, v37, v37
	v_pk_mul_f32 v[40:41], v[32:33], v[32:33]
	v_max_f32_e32 v33, v34, v34
	v_max_f32_e32 v32, v38, v38
	v_max_f32_e32 v34, 0, v33
	v_max_f32_e32 v33, v39, v39
	v_max_f32_e32 v35, v35, v35
	v_max_f32_e32 v36, 0, v36
	v_max_f32_e32 v37, 0, v37
	v_max_f32_e32 v32, 0, v32
	v_max_f32_e32 v33, 0, v33
	v_max_f32_e32 v35, 0, v35
	s_mov_b64 s[48:49], 0x120000
	v_pk_mul_f32 v[36:37], v[36:37], v[36:37]
	v_pk_mul_f32 v[38:39], v[32:33], v[32:33]
	v_pk_mul_f32 v[42:43], v[34:35], v[34:35]
	v_max_f32_e32 v24, v24, v24
	v_max_f32_e32 v25, v25, v25
	v_lshl_add_u64 v[48:49], v[144:145], 0, s[48:49]
	v_cvt_pk_bf16_f32 v32, v36, v37
	v_cvt_pk_bf16_f32 v33, v38, v39
	v_cvt_pk_bf16_f32 v34, v40, v41
	v_cvt_pk_bf16_f32 v35, v42, v43
	v_max_f32_e32 v24, 0, v24
	v_max_f32_e32 v25, 0, v25
	global_store_dwordx4 v[48:49], v[32:35], off offset:256 sc1
	v_max_f32_e32 v28, v28, v28
	v_max_f32_e32 v29, v29, v29
	v_pk_mul_f32 v[34:35], v[24:25], v[24:25]
	v_max_f32_e32 v25, v26, v26
	v_max_f32_e32 v28, 0, v28
	v_max_f32_e32 v29, 0, v29
	v_max_f32_e32 v24, v30, v30
	v_max_f32_e32 v26, 0, v25
	v_max_f32_e32 v25, v31, v31
	v_max_f32_e32 v27, v27, v27
	v_pk_mul_f32 v[28:29], v[28:29], v[28:29]
	v_max_f32_e32 v24, 0, v24
	v_max_f32_e32 v25, 0, v25
	v_max_f32_e32 v27, 0, v27
	s_mov_b32 s17, 0x140000
	v_pk_mul_f32 v[30:31], v[24:25], v[24:25]
	v_pk_mul_f32 v[36:37], v[26:27], v[26:27]
	v_cvt_pk_bf16_f32 v24, v28, v29
	v_add_co_u32_e32 v28, vcc, s17, v144
	v_max_f32_e32 v16, v16, v16
	v_max_f32_e32 v17, v17, v17
	v_cvt_pk_bf16_f32 v25, v30, v31
	v_cvt_pk_bf16_f32 v26, v34, v35
	v_cvt_pk_bf16_f32 v27, v36, v37
	v_addc_co_u32_e32 v29, vcc, 0, v145, vcc
	v_max_f32_e32 v16, 0, v16
	v_max_f32_e32 v17, 0, v17
	global_store_dwordx4 v[28:29], v[24:27], off sc1
	v_max_f32_e32 v20, v20, v20
	v_max_f32_e32 v21, v21, v21
	v_pk_mul_f32 v[24:25], v[16:17], v[16:17]
	v_max_f32_e32 v17, v18, v18
	v_max_f32_e32 v16, v22, v22
	v_max_f32_e32 v18, 0, v17
	v_max_f32_e32 v17, v23, v23
	v_max_f32_e32 v19, v19, v19
	v_max_f32_e32 v20, 0, v20
	v_max_f32_e32 v21, 0, v21
	v_max_f32_e32 v16, 0, v16
	v_max_f32_e32 v17, 0, v17
	v_max_f32_e32 v19, 0, v19
	s_mov_b64 s[48:49], 0x140000
	v_pk_mul_f32 v[20:21], v[20:21], v[20:21]
	v_pk_mul_f32 v[22:23], v[16:17], v[16:17]
	v_pk_mul_f32 v[26:27], v[18:19], v[18:19]
	v_max_f32_e32 v8, v8, v8
	v_max_f32_e32 v9, v9, v9
	v_lshl_add_u64 v[32:33], v[144:145], 0, s[48:49]
	v_cvt_pk_bf16_f32 v16, v20, v21
	v_cvt_pk_bf16_f32 v17, v22, v23
	v_cvt_pk_bf16_f32 v18, v24, v25
	v_cvt_pk_bf16_f32 v19, v26, v27
	v_max_f32_e32 v8, 0, v8
	v_max_f32_e32 v9, 0, v9
	global_store_dwordx4 v[32:33], v[16:19], off offset:256 sc1
	v_max_f32_e32 v12, v12, v12
	v_max_f32_e32 v13, v13, v13
	v_pk_mul_f32 v[18:19], v[8:9], v[8:9]
	v_max_f32_e32 v9, v10, v10
	v_max_f32_e32 v12, 0, v12
	v_max_f32_e32 v13, 0, v13
	v_max_f32_e32 v8, v14, v14
	v_max_f32_e32 v10, 0, v9
	v_max_f32_e32 v9, v15, v15
	v_max_f32_e32 v11, v11, v11
	v_pk_mul_f32 v[12:13], v[12:13], v[12:13]
	v_max_f32_e32 v8, 0, v8
	v_max_f32_e32 v9, 0, v9
	v_max_f32_e32 v11, 0, v11
	v_pk_mul_f32 v[14:15], v[8:9], v[8:9]
	v_pk_mul_f32 v[20:21], v[10:11], v[10:11]
	v_cvt_pk_bf16_f32 v8, v12, v13
	v_add_co_u32_e32 v12, vcc, s45, v144
	v_max_f32_e32 v0, v0, v0
	v_max_f32_e32 v1, v1, v1
	v_cvt_pk_bf16_f32 v9, v14, v15
	v_cvt_pk_bf16_f32 v10, v18, v19
	v_cvt_pk_bf16_f32 v11, v20, v21
	v_addc_co_u32_e32 v13, vcc, 0, v145, vcc
	v_max_f32_e32 v0, 0, v0
	v_max_f32_e32 v1, 0, v1
	global_store_dwordx4 v[12:13], v[8:11], off sc1
	v_max_f32_e32 v4, v4, v4
	v_max_f32_e32 v5, v5, v5
	v_pk_mul_f32 v[8:9], v[0:1], v[0:1]
	v_max_f32_e32 v1, v2, v2
	v_max_f32_e32 v0, v6, v6
	v_max_f32_e32 v2, 0, v1
	v_max_f32_e32 v1, v7, v7
	v_max_f32_e32 v3, v3, v3
	v_max_f32_e32 v4, 0, v4
	v_max_f32_e32 v5, 0, v5
	v_max_f32_e32 v0, 0, v0
	v_max_f32_e32 v1, 0, v1
	v_max_f32_e32 v3, 0, v3
	s_mov_b64 s[48:49], 0x160000
	v_pk_mul_f32 v[4:5], v[4:5], v[4:5]
	v_pk_mul_f32 v[6:7], v[0:1], v[0:1]
	v_pk_mul_f32 v[10:11], v[2:3], v[2:3]
	v_lshl_add_u64 v[16:17], v[144:145], 0, s[48:49]
	v_cvt_pk_bf16_f32 v0, v4, v5
	v_cvt_pk_bf16_f32 v1, v6, v7
	v_cvt_pk_bf16_f32 v2, v8, v9
	v_cvt_pk_bf16_f32 v3, v10, v11
	s_andn2_b64 vcc, exec, s[4:5]
	s_mov_b64 s[4:5], -1
	global_store_dwordx4 v[16:17], v[0:3], off offset:256 sc1
	s_cbranch_vccnz .LBB0_547
	s_andn2_b64 vcc, exec, s[8:9]
	s_cbranch_vccnz .LBB0_546
	s_barrier
	s_branch .LBB0_546
